# in-proj common epilogue: the 16 dwordx4 stores per tile in saddr form (SGPR base + 32-bit byte offset), 64-bit mad address chains removed
# speedup vs baseline: 1.0107x; 1.0107x over previous
.LBB0_297:
	v_add_u32_e32 v132, s41, v224
	v_mul_lo_u32 v134, s50, v216
	v_add_lshl_u32 v134, v134, v132, 1
	v_cvt_pk_bf16_f32 v128, v76, v77
	v_cvt_pk_bf16_f32 v129, v78, v79
	v_cvt_pk_bf16_f32 v130, v68, v69
	v_cvt_pk_bf16_f32 v131, v70, v71
	global_store_dwordx4 v134, v[128:131], s[52:53]
	s_nop 1
	v_cvt_pk_bf16_f32 v128, v124, v125
	v_cvt_pk_bf16_f32 v129, v126, v127
	v_cvt_pk_bf16_f32 v130, v120, v121
	v_cvt_pk_bf16_f32 v131, v122, v123
	global_store_dwordx4 v134, v[128:131], s[52:53] offset:256
	s_nop 1
	v_or_b32_e32 v128, 16, v216
	v_mul_lo_u32 v134, s50, v128
	v_add_lshl_u32 v134, v134, v132, 1
	v_cvt_pk_bf16_f32 v128, v60, v61
	v_cvt_pk_bf16_f32 v129, v62, v63
	v_cvt_pk_bf16_f32 v130, v56, v57
	v_cvt_pk_bf16_f32 v131, v58, v59
	global_store_dwordx4 v134, v[128:131], s[52:53]
	s_nop 1
	v_cvt_pk_bf16_f32 v128, v116, v117
	v_cvt_pk_bf16_f32 v129, v118, v119
	v_cvt_pk_bf16_f32 v130, v112, v113
	v_cvt_pk_bf16_f32 v131, v114, v115
	global_store_dwordx4 v134, v[128:131], s[52:53] offset:256
	s_nop 1
	v_or_b32_e32 v128, 32, v216
	v_mul_lo_u32 v134, s50, v128
	v_add_lshl_u32 v134, v134, v132, 1
	v_cvt_pk_bf16_f32 v128, v52, v53
	v_cvt_pk_bf16_f32 v129, v54, v55
	v_cvt_pk_bf16_f32 v130, v48, v49
	v_cvt_pk_bf16_f32 v131, v50, v51
	global_store_dwordx4 v134, v[128:131], s[52:53]
	s_nop 1
	v_cvt_pk_bf16_f32 v128, v108, v109
	v_cvt_pk_bf16_f32 v129, v110, v111
	v_cvt_pk_bf16_f32 v130, v104, v105
	v_cvt_pk_bf16_f32 v131, v106, v107
	global_store_dwordx4 v134, v[128:131], s[52:53] offset:256
	s_nop 1
	v_or_b32_e32 v128, 48, v216
	v_mul_lo_u32 v134, s50, v128
	v_add_lshl_u32 v134, v134, v132, 1
	v_cvt_pk_bf16_f32 v128, v44, v45
	v_cvt_pk_bf16_f32 v129, v46, v47
	v_cvt_pk_bf16_f32 v130, v40, v41
	v_cvt_pk_bf16_f32 v131, v42, v43
	global_store_dwordx4 v134, v[128:131], s[52:53]
	s_nop 1
	v_cvt_pk_bf16_f32 v128, v100, v101
	v_cvt_pk_bf16_f32 v129, v102, v103
	v_cvt_pk_bf16_f32 v130, v96, v97
	v_cvt_pk_bf16_f32 v131, v98, v99
	global_store_dwordx4 v134, v[128:131], s[52:53] offset:256
	s_nop 1
	v_add_u32_e32 v128, 0x80, v216
	v_mul_lo_u32 v134, s50, v128
	v_add_lshl_u32 v134, v134, v132, 1
	v_cvt_pk_bf16_f32 v128, v28, v29
	v_cvt_pk_bf16_f32 v129, v30, v31
	v_cvt_pk_bf16_f32 v130, v24, v25
	v_cvt_pk_bf16_f32 v131, v26, v27
	global_store_dwordx4 v134, v[128:131], s[52:53]
	s_nop 1
	v_cvt_pk_bf16_f32 v128, v92, v93
	v_cvt_pk_bf16_f32 v129, v94, v95
	v_cvt_pk_bf16_f32 v130, v88, v89
	v_cvt_pk_bf16_f32 v131, v90, v91
	global_store_dwordx4 v134, v[128:131], s[52:53] offset:256
	s_nop 1
	v_add_u32_e32 v128, 0x90, v216
	v_mul_lo_u32 v134, s50, v128
	v_add_lshl_u32 v134, v134, v132, 1
	v_cvt_pk_bf16_f32 v128, v20, v21
	v_cvt_pk_bf16_f32 v129, v22, v23
	v_cvt_pk_bf16_f32 v130, v16, v17
	v_cvt_pk_bf16_f32 v131, v18, v19
	global_store_dwordx4 v134, v[128:131], s[52:53]
	s_nop 1
	v_cvt_pk_bf16_f32 v128, v84, v85
	v_cvt_pk_bf16_f32 v129, v86, v87
	v_cvt_pk_bf16_f32 v130, v80, v81
	v_cvt_pk_bf16_f32 v131, v82, v83
	global_store_dwordx4 v134, v[128:131], s[52:53] offset:256
	s_nop 1
	v_add_u32_e32 v128, 0xa0, v216
	v_mul_lo_u32 v134, s50, v128
	v_add_lshl_u32 v134, v134, v132, 1
	v_cvt_pk_bf16_f32 v128, v12, v13
	v_cvt_pk_bf16_f32 v129, v14, v15
	v_cvt_pk_bf16_f32 v130, v8, v9
	v_cvt_pk_bf16_f32 v131, v10, v11
	global_store_dwordx4 v134, v[128:131], s[52:53]
	s_nop 1
	v_cvt_pk_bf16_f32 v128, v72, v73
	v_cvt_pk_bf16_f32 v129, v74, v75
	v_cvt_pk_bf16_f32 v130, v64, v65
	v_cvt_pk_bf16_f32 v131, v66, v67
	global_store_dwordx4 v134, v[128:131], s[52:53] offset:256
	s_nop 1
	v_add_u32_e32 v128, 0xb0, v216
	v_mul_lo_u32 v134, s50, v128
	v_add_lshl_u32 v134, v134, v132, 1
	v_cvt_pk_bf16_f32 v128, v4, v5
	v_cvt_pk_bf16_f32 v129, v6, v7
	v_cvt_pk_bf16_f32 v130, v0, v1
	v_cvt_pk_bf16_f32 v131, v2, v3
	global_store_dwordx4 v134, v[128:131], s[52:53]
	s_mov_b64 s[50:51], 0
	s_nop 0
	v_cvt_pk_bf16_f32 v128, v36, v37
	v_cvt_pk_bf16_f32 v129, v38, v39
	v_cvt_pk_bf16_f32 v130, v32, v33
	v_cvt_pk_bf16_f32 v131, v34, v35
	global_store_dwordx4 v134, v[128:131], s[52:53] offset:256
